# diff-attention main loop: first two PV MFMAs of each tile issued inside the row-max chain (independent of it), waits recounted
# baseline (speedup 1.0000x reference)
.LBB0_477:
	s_lshl_b32 s22, s22, 1
	v_add_u32_e32 v212, s22, v245
	ds_read_b64_tr_b16 v[208:209], v212 offset:24576
	ds_read_b64_tr_b16 v[210:211], v212 offset:25088
	v_mfma_f32_32x32x16_bf16 v[128:143], v[204:207], v[172:175], v[64:79]
	v_add_f32_e32 v112, v96, v97
	v_add_f32_e32 v112, v98, v112
	v_add_f32_e32 v112, v99, v112
	v_add_f32_e32 v112, v100, v112
	v_add_f32_e32 v112, v101, v112
	v_cvt_pk_bf16_f32 v156, v96, v97
	v_cvt_pk_bf16_f32 v157, v98, v99
	ds_read_b64_tr_b16 v[204:205], v212 offset:28672
	ds_read_b64_tr_b16 v[206:207], v212 offset:29184
	v_add_f32_e32 v96, v102, v112
	v_mfma_f32_32x32x16_bf16 v[112:127], v[196:199], v[172:175], v[64:79]
	v_add_f32_e32 v96, v103, v96
	v_add_f32_e32 v96, v104, v96
	v_add_f32_e32 v96, v105, v96
	v_cvt_pk_bf16_f32 v158, v100, v101
	v_cvt_pk_bf16_f32 v159, v102, v103
	ds_read_b64_tr_b16 v[100:101], v212 offset:25600
	ds_read_b64_tr_b16 v[102:103], v212 offset:26112
	v_mfma_f32_32x32x16_bf16 v[128:143], v[200:203], v[168:171], v[128:143]
	v_add_f32_e32 v96, v106, v96
	v_add_f32_e32 v96, v107, v96
	v_add_f32_e32 v96, v108, v96
	v_add_f32_e32 v144, v109, v96
	v_cvt_pk_bf16_f32 v152, v104, v105
	v_cvt_pk_bf16_f32 v153, v106, v107
	ds_read_b64_tr_b16 v[96:97], v212 offset:29696
	ds_read_b64_tr_b16 v[98:99], v212 offset:30208
	v_mfma_f32_32x32x16_bf16 v[112:127], v[192:195], v[168:171], v[112:127]
	v_add_f32_e32 v104, v110, v144
	v_add_f32_e32 v104, v111, v104
	v_add_f32_e32 v104, v80, v104
	v_add_f32_e32 v104, v81, v104
	v_cvt_pk_bf16_f32 v154, v108, v109
	v_cvt_pk_bf16_f32 v155, v110, v111
	ds_read_b64_tr_b16 v[108:109], v212 offset:26624
	ds_read_b64_tr_b16 v[110:111], v212 offset:27136
	v_mfma_f32_32x32x16_bf16 v[128:143], v[188:191], v[164:167], v[128:143]
	v_add_f32_e32 v104, v82, v104
	v_add_f32_e32 v104, v83, v104
	v_add_f32_e32 v104, v84, v104
	v_add_f32_e32 v144, v85, v104
	v_cvt_pk_bf16_f32 v148, v80, v81
	v_cvt_pk_bf16_f32 v149, v82, v83
	ds_read_b64_tr_b16 v[104:105], v212 offset:30720
	ds_read_b64_tr_b16 v[106:107], v212 offset:31232
	v_mfma_f32_32x32x16_bf16 v[112:127], v[184:187], v[164:167], v[112:127]
	v_add_f32_e32 v80, v86, v144
	v_add_f32_e32 v80, v87, v80
	v_add_f32_e32 v80, v88, v80
	v_add_f32_e32 v80, v89, v80
	v_cvt_pk_bf16_f32 v150, v84, v85
	v_cvt_pk_bf16_f32 v151, v86, v87
	ds_read_b64_tr_b16 v[84:85], v212 offset:27648
	ds_read_b64_tr_b16 v[86:87], v212 offset:28160
	v_mfma_f32_32x32x16_bf16 v[128:143], v[180:183], v[160:163], v[128:143]
	v_add_f32_e32 v80, v90, v80
	v_add_f32_e32 v80, v91, v80
	v_add_f32_e32 v80, v92, v80
	v_add_f32_e32 v80, v93, v80
	v_cvt_pk_bf16_f32 v144, v88, v89
	v_cvt_pk_bf16_f32 v145, v90, v91
	ds_read_b64_tr_b16 v[88:89], v212 offset:31744
	ds_read_b64_tr_b16 v[90:91], v212 offset:32256
	v_mfma_f32_32x32x16_bf16 v[112:127], v[176:179], v[160:163], v[112:127]
	v_add_f32_e32 v80, v94, v80
	v_add_f32_e32 v80, v95, v80
	v_cvt_pk_bf16_f32 v146, v92, v93
	v_cvt_pk_bf16_f32 v147, v94, v95
	s_waitcnt lgkmcnt(14)
	v_mfma_f32_32x32x16_bf16 v[0:15], v[156:159], v[208:211], v[0:15]
	v_max_f32_e32 v81, v129, v129
	v_max_f32_e32 v82, v128, v128
	v_max_f32_e32 v81, v82, v81
	s_nop 3
	v_max3_f32 v82, v130, v131, v113
	v_max3_f32 v81, v81, v112, v114
	v_max3_f32 v81, v81, v115, v132
	v_max3_f32 v82, v82, v134, v135
	s_waitcnt lgkmcnt(12)
	v_mfma_f32_32x32x16_bf16 v[48:63], v[156:159], v[204:207], v[48:63]
	s_add_u32 s37, s16, s24
	v_max3_f32 v81, v81, v133, v116
	v_max3_f32 v82, v82, v118, v119
	s_addc_u32 s39, s17, s19
	v_max3_f32 v81, v81, v117, v136
	v_max3_f32 v82, v82, v138, v139
	s_add_u32 s22, s37, 0x9b80800
	v_max3_f32 v81, v81, v137, v120
	v_max3_f32 v82, v82, v122, v123
	s_addc_u32 s23, s39, 0
	s_add_i32 s34, s33, s28
	s_mov_b32 m0, s34
	s_nop 0
	global_load_lds_dwordx4 v241, s[22:23]
	v_max3_f32 v81, v81, v121, v140
	v_max3_f32 v82, v82, v142, v143
	s_add_u32 s35, s20, s24
	v_max3_f32 v81, v81, v141, v124
	v_max3_f32 v82, v82, v126, v127
	s_addc_u32 s36, s21, s19
	v_add_f32_e32 v251, v251, v80
	v_max3_f32 v80, v81, v125, v82
	s_add_u32 s22, s35, 0x9ac1000
	v_mov_b32_e32 v81, v80
	s_addc_u32 s23, s36, 0
	s_lshl_b32 s34, s31, 1
	v_permlane32_swap_b32_e32 v80, v81
	s_add_i32 s34, s34, s29
	v_max_f32_e32 v81, v81, v81
	v_max_f32_e32 v80, v80, v80
	s_mov_b32 m0, s34
	s_nop 0
	global_load_lds_dwordx4 v242, s[22:23]
	s_add_u32 s22, s35, 0x9ac1080
	v_max_f32_e32 v80, v80, v81
	s_addc_u32 s23, s36, 0
	s_addk_i32 s34, 0x2000
	s_mov_b32 m0, s34
	s_nop 0
	global_load_lds_dwordx4 v242, s[22:23]
	v_cmp_lt_f32_e32 vcc, s25, v80
	s_cmp_lg_u64 vcc, 0
	s_cselect_b64 s[22:23], -1, 0
	s_cbranch_vccnz .LBB0_485
.LBB0_478:
	v_exp_f32_e32 v128, v128
	v_exp_f32_e32 v129, v129
	ds_read_b64_tr_b16 v[92:93], v212 offset:32768
	ds_read_b64_tr_b16 v[94:95], v212 offset:33280
	v_exp_f32_e32 v132, v132
	v_exp_f32_e32 v133, v133
	ds_read_b64_tr_b16 v[204:205], v212 offset:36864
	ds_read_b64_tr_b16 v[206:207], v212 offset:37376
	v_add_u32_e32 v176, s31, v243
	ds_read_b128 v[80:83], v176
	ds_read_b128 v[196:199], v176 offset:512
	s_waitcnt lgkmcnt(14)
	v_mfma_f32_32x32x16_bf16 v[0:15], v[152:155], v[100:103], v[0:15]
	v_exp_f32_e32 v136, v136
	v_exp_f32_e32 v137, v137
	ds_read_b64_tr_b16 v[100:101], v212 offset:33792
	ds_read_b64_tr_b16 v[102:103], v212 offset:34304
	ds_read_b128 v[200:203], v176 offset:2048
	ds_read_b128 v[192:195], v176 offset:2560
	v_mfma_f32_32x32x16_bf16 v[48:63], v[152:155], v[96:99], v[48:63]
	v_exp_f32_e32 v140, v140
	v_exp_f32_e32 v141, v141
	ds_read_b64_tr_b16 v[96:97], v212 offset:37888
	ds_read_b64_tr_b16 v[98:99], v212 offset:38400
	ds_read_b128 v[188:191], v176 offset:4096
	ds_read_b128 v[184:187], v176 offset:4608
	s_waitcnt lgkmcnt(14)
	v_mfma_f32_32x32x16_bf16 v[0:15], v[148:151], v[108:111], v[0:15]
	v_exp_f32_e32 v112, v112
	v_exp_f32_e32 v113, v113
	ds_read_b64_tr_b16 v[108:109], v212 offset:34816
	ds_read_b64_tr_b16 v[110:111], v212 offset:35328
	ds_read_b128 v[180:183], v176 offset:6144
	ds_read_b128 v[176:179], v176 offset:6656
	v_mfma_f32_32x32x16_bf16 v[48:63], v[148:151], v[104:107], v[48:63]
	v_exp_f32_e32 v116, v116
	v_exp_f32_e32 v117, v117
	ds_read_b64_tr_b16 v[104:105], v212 offset:38912
	ds_read_b64_tr_b16 v[106:107], v212 offset:39424
	v_mfma_f32_32x32x16_bf16 v[0:15], v[144:147], v[84:87], v[0:15]
	v_exp_f32_e32 v120, v120
	v_exp_f32_e32 v121, v121
	ds_read_b64_tr_b16 v[84:85], v212 offset:35840
	ds_read_b64_tr_b16 v[86:87], v212 offset:36352
	v_mfma_f32_32x32x16_bf16 v[48:63], v[144:147], v[88:91], v[48:63]
	v_exp_f32_e32 v124, v124
	v_exp_f32_e32 v125, v125
	ds_read_b64_tr_b16 v[88:89], v212 offset:39936
	ds_read_b64_tr_b16 v[90:91], v212 offset:40448
	s_waitcnt lgkmcnt(14)
	v_mfma_f32_32x32x16_bf16 v[16:31], v[156:159], v[92:95], v[16:31]
	v_exp_f32_e32 v130, v130
	v_exp_f32_e32 v131, v131
	v_mfma_f32_32x32x16_bf16 v[32:47], v[156:159], v[204:207], v[32:47]
	v_exp_f32_e32 v134, v134
	v_exp_f32_e32 v135, v135
	v_mfma_f32_32x32x16_bf16 v[16:31], v[152:155], v[100:103], v[16:31]
	v_exp_f32_e32 v138, v138
	v_exp_f32_e32 v139, v139
	s_waitcnt lgkmcnt(12)
	v_mfma_f32_32x32x16_bf16 v[32:47], v[152:155], v[96:99], v[32:47]
	v_exp_f32_e32 v142, v142
	v_exp_f32_e32 v143, v143
	s_waitcnt lgkmcnt(8)
	v_mfma_f32_32x32x16_bf16 v[16:31], v[148:151], v[108:111], v[16:31]
	v_exp_f32_e32 v114, v114
	v_exp_f32_e32 v115, v115
	s_waitcnt lgkmcnt(4)
	v_mfma_f32_32x32x16_bf16 v[32:47], v[148:151], v[104:107], v[32:47]
	v_exp_f32_e32 v118, v118
	v_exp_f32_e32 v119, v119
	s_waitcnt lgkmcnt(2)
	v_mfma_f32_32x32x16_bf16 v[16:31], v[144:147], v[84:87], v[16:31]
	v_exp_f32_e32 v122, v122
	v_exp_f32_e32 v123, v123
	s_waitcnt lgkmcnt(0)
	v_mfma_f32_32x32x16_bf16 v[32:47], v[144:147], v[88:91], v[32:47]
	v_exp_f32_e32 v126, v126
	v_exp_f32_e32 v127, v127
	s_waitcnt vmcnt(3) lgkmcnt(0)
	s_barrier
	s_andn2_b64 vcc, exec, s[22:23]
	s_cbranch_vccnz .LBB0_480
	s_waitcnt lgkmcnt(0)
	v_add_u32_e32 v96, s18, v247
	ds_read_b128 v[84:87], v96 offset:96
	ds_read_b128 v[88:91], v96 offset:64
	ds_read_b128 v[92:95], v96 offset:32
	ds_read_b128 v[96:99], v96
	s_waitcnt lgkmcnt(3)
	v_pk_mul_f32 v[12:13], v[12:13], v[84:85]
	s_waitcnt lgkmcnt(2)
	v_pk_mul_f32 v[8:9], v[8:9], v[88:89]
	s_waitcnt lgkmcnt(1)
	v_pk_mul_f32 v[4:5], v[4:5], v[92:93]
	v_pk_mul_f32 v[14:15], v[14:15], v[86:87]
	v_pk_mul_f32 v[10:11], v[10:11], v[90:91]
	v_pk_mul_f32 v[6:7], v[6:7], v[94:95]
	s_waitcnt lgkmcnt(0)
	v_pk_mul_f32 v[2:3], v[2:3], v[98:99]
	v_pk_mul_f32 v[0:1], v[0:1], v[96:97]
	v_pk_mul_f32 v[60:61], v[60:61], v[84:85]
	v_pk_mul_f32 v[56:57], v[56:57], v[88:89]
	v_pk_mul_f32 v[52:53], v[52:53], v[92:93]
	v_pk_mul_f32 v[62:63], v[62:63], v[86:87]
	v_pk_mul_f32 v[58:59], v[58:59], v[90:91]
	v_pk_mul_f32 v[54:55], v[54:55], v[94:95]
	v_pk_mul_f32 v[50:51], v[50:51], v[98:99]
	v_pk_mul_f32 v[48:49], v[48:49], v[96:97]
	v_pk_mul_f32 v[28:29], v[28:29], v[84:85]
	v_pk_mul_f32 v[24:25], v[24:25], v[88:89]
	v_pk_mul_f32 v[20:21], v[20:21], v[92:93]
	v_pk_mul_f32 v[30:31], v[30:31], v[86:87]
	v_pk_mul_f32 v[26:27], v[26:27], v[90:91]
	v_pk_mul_f32 v[22:23], v[22:23], v[94:95]
	v_pk_mul_f32 v[18:19], v[18:19], v[98:99]
	v_pk_mul_f32 v[16:17], v[16:17], v[96:97]
	v_pk_mul_f32 v[44:45], v[44:45], v[84:85]
	v_pk_mul_f32 v[40:41], v[40:41], v[88:89]
	v_pk_mul_f32 v[36:37], v[36:37], v[92:93]
	v_pk_mul_f32 v[46:47], v[46:47], v[86:87]
	v_pk_mul_f32 v[42:43], v[42:43], v[90:91]
	v_pk_mul_f32 v[38:39], v[38:39], v[94:95]
	v_pk_mul_f32 v[34:35], v[34:35], v[98:99]
	v_pk_mul_f32 v[32:33], v[32:33], v[96:97]
.LBB0_480:
	s_add_i32 s22, s31, 0x2000
	s_cmpk_lg_i32 s31, 0x4000
	s_cselect_b32 s34, s22, 0
	s_lshl_b32 s22, s33, 1
	v_add_u32_e32 v236, s22, v245
	ds_read_b64_tr_b16 v[212:213], v236 offset:24576
	ds_read_b64_tr_b16 v[214:215], v236 offset:25088
	v_mfma_f32_32x32x16_bf16 v[96:111], v[80:83], v[172:175], v[64:79]
	v_add_f32_e32 v84, v128, v129
	v_add_f32_e32 v84, v130, v84
	v_add_f32_e32 v84, v131, v84
	v_add_f32_e32 v84, v132, v84
	v_add_f32_e32 v84, v133, v84
	v_cvt_pk_bf16_f32 v156, v128, v129
	v_cvt_pk_bf16_f32 v157, v130, v131
	ds_read_b64_tr_b16 v[204:205], v236 offset:28672
	ds_read_b64_tr_b16 v[206:207], v236 offset:29184
	v_add_f32_e32 v80, v134, v84
	v_add_f32_e32 v80, v135, v80
	v_add_f32_e32 v80, v136, v80
	v_add_f32_e32 v128, v137, v80
	v_mfma_f32_32x32x16_bf16 v[80:95], v[196:199], v[172:175], v[64:79]
	v_cvt_pk_bf16_f32 v158, v132, v133
	v_cvt_pk_bf16_f32 v159, v134, v135
	ds_read_b64_tr_b16 v[208:209], v236 offset:25600
	ds_read_b64_tr_b16 v[210:211], v236 offset:26112
	v_mfma_f32_32x32x16_bf16 v[96:111], v[200:203], v[168:171], v[96:111]
	v_add_f32_e32 v128, v138, v128
	v_add_f32_e32 v128, v139, v128
	v_add_f32_e32 v128, v140, v128
	v_add_f32_e32 v128, v141, v128
	v_cvt_pk_bf16_f32 v152, v136, v137
	v_cvt_pk_bf16_f32 v153, v138, v139
	ds_read_b64_tr_b16 v[132:133], v236 offset:29696
	ds_read_b64_tr_b16 v[134:135], v236 offset:30208
	v_mfma_f32_32x32x16_bf16 v[80:95], v[192:195], v[168:171], v[80:95]
	v_add_f32_e32 v128, v142, v128
	v_add_f32_e32 v128, v143, v128
	v_add_f32_e32 v128, v112, v128
	v_add_f32_e32 v136, v113, v128
	v_cvt_pk_bf16_f32 v154, v140, v141
	v_cvt_pk_bf16_f32 v155, v142, v143
	ds_read_b64_tr_b16 v[128:129], v236 offset:26624
	ds_read_b64_tr_b16 v[130:131], v236 offset:27136
	v_mfma_f32_32x32x16_bf16 v[96:111], v[188:191], v[164:167], v[96:111]
	v_add_f32_e32 v136, v114, v136
	v_add_f32_e32 v136, v115, v136
	v_add_f32_e32 v136, v116, v136
	v_add_f32_e32 v136, v117, v136
	v_cvt_pk_bf16_f32 v148, v112, v113
	v_cvt_pk_bf16_f32 v149, v114, v115
	ds_read_b64_tr_b16 v[112:113], v236 offset:30720
	ds_read_b64_tr_b16 v[114:115], v236 offset:31232
	v_mfma_f32_32x32x16_bf16 v[80:95], v[184:187], v[164:167], v[80:95]
	v_add_f32_e32 v136, v118, v136
	v_add_f32_e32 v136, v119, v136
	v_add_f32_e32 v136, v120, v136
	v_add_f32_e32 v136, v121, v136
	v_cvt_pk_bf16_f32 v150, v116, v117
	v_cvt_pk_bf16_f32 v151, v118, v119
	ds_read_b64_tr_b16 v[116:117], v236 offset:27648
	ds_read_b64_tr_b16 v[118:119], v236 offset:28160
	v_mfma_f32_32x32x16_bf16 v[96:111], v[180:183], v[160:163], v[96:111]
	v_add_f32_e32 v136, v122, v136
	v_add_f32_e32 v136, v123, v136
	v_add_f32_e32 v136, v124, v136
	v_add_f32_e32 v136, v125, v136
	v_cvt_pk_bf16_f32 v144, v120, v121
	v_cvt_pk_bf16_f32 v145, v122, v123
	ds_read_b64_tr_b16 v[120:121], v236 offset:31744
	ds_read_b64_tr_b16 v[122:123], v236 offset:32256
	v_mfma_f32_32x32x16_bf16 v[80:95], v[176:179], v[160:163], v[80:95]
	v_add_f32_e32 v136, v126, v136
	v_add_f32_e32 v136, v127, v136
	v_cvt_pk_bf16_f32 v146, v124, v125
	v_cvt_pk_bf16_f32 v147, v126, v127
	s_waitcnt lgkmcnt(14)
	v_mfma_f32_32x32x16_bf16 v[0:15], v[156:159], v[212:215], v[0:15]
	v_max_f32_e32 v124, v97, v97
	v_max_f32_e32 v125, v96, v96
	v_max_f32_e32 v124, v125, v124
	s_nop 3
	v_max3_f32 v125, v98, v99, v81
	v_max3_f32 v124, v124, v80, v82
	v_max3_f32 v124, v124, v83, v100
	v_max3_f32 v125, v125, v102, v103
	s_waitcnt lgkmcnt(12)
	v_mfma_f32_32x32x16_bf16 v[48:63], v[156:159], v[204:207], v[48:63]
	v_max3_f32 v124, v124, v101, v84
	v_max3_f32 v125, v125, v86, v87
	v_max3_f32 v124, v124, v85, v104
	v_max3_f32 v125, v125, v106, v107
	v_max3_f32 v124, v124, v105, v88
	v_max3_f32 v125, v125, v90, v91
	v_max3_f32 v124, v124, v89, v108
	v_max3_f32 v125, v125, v110, v111
	s_add_u32 s22, s37, 0x9be0800
	v_max3_f32 v124, v124, v109, v92
	v_max3_f32 v125, v125, v94, v95
	s_addc_u32 s23, s39, 0
	s_add_i32 s33, s31, s28
	v_max3_f32 v124, v124, v93, v125
	s_mov_b32 m0, s33
	s_nop 0
	global_load_lds_dwordx4 v241, s[22:23]
	s_add_u32 s22, s35, 0x9b21000
	v_mov_b32_e32 v125, v124
	s_addc_u32 s23, s36, 0
	s_lshl_b32 s33, s34, 1
	v_permlane32_swap_b32_e32 v124, v125
	s_add_i32 s33, s33, s29
	v_max_f32_e32 v125, v125, v125
	v_max_f32_e32 v124, v124, v124
	s_mov_b32 m0, s33
	s_nop 0
	global_load_lds_dwordx4 v242, s[22:23]
	s_add_u32 s22, s35, 0x9b21080
	v_max_f32_e32 v124, v124, v125
	s_addc_u32 s23, s36, 0
	s_addk_i32 s33, 0x2000
	s_mov_b32 m0, s33
	s_nop 0
	global_load_lds_dwordx4 v242, s[22:23]
	v_cmp_lt_f32_e32 vcc, s25, v124
	s_cmp_lg_u64 vcc, 0
	v_add_f32_e32 v251, v251, v136
	s_cselect_b64 s[22:23], -1, 0
	s_cbranch_vccnz .LBB0_488
.LBB0_481:
	v_exp_f32_e32 v96, v96
	v_exp_f32_e32 v97, v97
	ds_read_b64_tr_b16 v[124:125], v236 offset:32768
	ds_read_b64_tr_b16 v[126:127], v236 offset:33280
	v_exp_f32_e32 v100, v100
	v_exp_f32_e32 v101, v101
	ds_read_b64_tr_b16 v[136:137], v236 offset:36864
	ds_read_b64_tr_b16 v[138:139], v236 offset:37376
	v_add_u32_e32 v176, s34, v243
	ds_read_b128 v[204:207], v176
	ds_read_b128 v[196:199], v176 offset:512
	s_waitcnt lgkmcnt(14)
	v_mfma_f32_32x32x16_bf16 v[0:15], v[152:155], v[208:211], v[0:15]
	v_exp_f32_e32 v104, v104
	v_exp_f32_e32 v105, v105
	ds_read_b64_tr_b16 v[140:141], v236 offset:33792
	ds_read_b64_tr_b16 v[142:143], v236 offset:34304
	ds_read_b128 v[200:203], v176 offset:2048
	ds_read_b128 v[192:195], v176 offset:2560
	v_mfma_f32_32x32x16_bf16 v[48:63], v[152:155], v[132:135], v[48:63]
	v_exp_f32_e32 v108, v108
	v_exp_f32_e32 v109, v109
	ds_read_b64_tr_b16 v[132:133], v236 offset:37888
	ds_read_b64_tr_b16 v[134:135], v236 offset:38400
	ds_read_b128 v[188:191], v176 offset:4096
	ds_read_b128 v[184:187], v176 offset:4608
	s_waitcnt lgkmcnt(14)
	v_mfma_f32_32x32x16_bf16 v[0:15], v[148:151], v[128:131], v[0:15]
	v_exp_f32_e32 v80, v80
	v_exp_f32_e32 v81, v81
	ds_read_b64_tr_b16 v[128:129], v236 offset:34816
	ds_read_b64_tr_b16 v[130:131], v236 offset:35328
	ds_read_b128 v[180:183], v176 offset:6144
	ds_read_b128 v[176:179], v176 offset:6656
	v_mfma_f32_32x32x16_bf16 v[48:63], v[148:151], v[112:115], v[48:63]
	v_exp_f32_e32 v84, v84
	v_exp_f32_e32 v85, v85
	ds_read_b64_tr_b16 v[112:113], v236 offset:38912
	ds_read_b64_tr_b16 v[114:115], v236 offset:39424
	v_mfma_f32_32x32x16_bf16 v[0:15], v[144:147], v[116:119], v[0:15]
	v_exp_f32_e32 v88, v88
	v_exp_f32_e32 v89, v89
	ds_read_b64_tr_b16 v[116:117], v236 offset:35840
	ds_read_b64_tr_b16 v[118:119], v236 offset:36352
	v_mfma_f32_32x32x16_bf16 v[48:63], v[144:147], v[120:123], v[48:63]
	v_exp_f32_e32 v92, v92
	v_exp_f32_e32 v93, v93
	ds_read_b64_tr_b16 v[120:121], v236 offset:39936
	ds_read_b64_tr_b16 v[122:123], v236 offset:40448
	s_waitcnt lgkmcnt(14)
	v_mfma_f32_32x32x16_bf16 v[16:31], v[156:159], v[124:127], v[16:31]
	v_exp_f32_e32 v98, v98
	v_exp_f32_e32 v99, v99
	v_mfma_f32_32x32x16_bf16 v[32:47], v[156:159], v[136:139], v[32:47]
	v_exp_f32_e32 v102, v102
	v_exp_f32_e32 v103, v103
	v_mfma_f32_32x32x16_bf16 v[16:31], v[152:155], v[140:143], v[16:31]
	v_exp_f32_e32 v106, v106
	v_exp_f32_e32 v107, v107
	s_waitcnt lgkmcnt(12)
	v_mfma_f32_32x32x16_bf16 v[32:47], v[152:155], v[132:135], v[32:47]
	v_exp_f32_e32 v110, v110
	v_exp_f32_e32 v111, v111
	s_waitcnt lgkmcnt(8)
	v_mfma_f32_32x32x16_bf16 v[16:31], v[148:151], v[128:131], v[16:31]
	v_exp_f32_e32 v82, v82
	v_exp_f32_e32 v83, v83
	s_waitcnt lgkmcnt(4)
	v_mfma_f32_32x32x16_bf16 v[32:47], v[148:151], v[112:115], v[32:47]
	v_exp_f32_e32 v86, v86
	v_exp_f32_e32 v87, v87
	s_waitcnt lgkmcnt(2)
	v_mfma_f32_32x32x16_bf16 v[16:31], v[144:147], v[116:119], v[16:31]
	v_exp_f32_e32 v90, v90
	v_exp_f32_e32 v91, v91
	s_waitcnt lgkmcnt(0)
	v_mfma_f32_32x32x16_bf16 v[32:47], v[144:147], v[120:123], v[32:47]
	v_exp_f32_e32 v94, v94
	v_exp_f32_e32 v95, v95
	s_waitcnt vmcnt(3) lgkmcnt(0)
	s_barrier
	s_andn2_b64 vcc, exec, s[22:23]
	s_cbranch_vccnz .LBB0_483
	s_waitcnt lgkmcnt(0)
	v_add_u32_e32 v124, s18, v247
	ds_read_b128 v[112:115], v124 offset:96
	ds_read_b128 v[116:119], v124 offset:64
	ds_read_b128 v[120:123], v124 offset:32
	ds_read_b128 v[124:127], v124
	s_waitcnt lgkmcnt(3)
	v_pk_mul_f32 v[12:13], v[12:13], v[112:113]
	s_waitcnt lgkmcnt(2)
	v_pk_mul_f32 v[8:9], v[8:9], v[116:117]
	s_waitcnt lgkmcnt(1)
	v_pk_mul_f32 v[4:5], v[4:5], v[120:121]
	v_pk_mul_f32 v[14:15], v[14:15], v[114:115]
	v_pk_mul_f32 v[10:11], v[10:11], v[118:119]
	v_pk_mul_f32 v[6:7], v[6:7], v[122:123]
	s_waitcnt lgkmcnt(0)
	v_pk_mul_f32 v[2:3], v[2:3], v[126:127]
	v_pk_mul_f32 v[0:1], v[0:1], v[124:125]
	v_pk_mul_f32 v[60:61], v[60:61], v[112:113]
	v_pk_mul_f32 v[56:57], v[56:57], v[116:117]
	v_pk_mul_f32 v[52:53], v[52:53], v[120:121]
	v_pk_mul_f32 v[62:63], v[62:63], v[114:115]
	v_pk_mul_f32 v[58:59], v[58:59], v[118:119]
	v_pk_mul_f32 v[54:55], v[54:55], v[122:123]
	v_pk_mul_f32 v[50:51], v[50:51], v[126:127]
	v_pk_mul_f32 v[48:49], v[48:49], v[124:125]
	v_pk_mul_f32 v[28:29], v[28:29], v[112:113]
	v_pk_mul_f32 v[24:25], v[24:25], v[116:117]
	v_pk_mul_f32 v[20:21], v[20:21], v[120:121]
	v_pk_mul_f32 v[30:31], v[30:31], v[114:115]
	v_pk_mul_f32 v[26:27], v[26:27], v[118:119]
	v_pk_mul_f32 v[22:23], v[22:23], v[122:123]
	v_pk_mul_f32 v[18:19], v[18:19], v[126:127]
	v_pk_mul_f32 v[16:17], v[16:17], v[124:125]
	v_pk_mul_f32 v[44:45], v[44:45], v[112:113]
	v_pk_mul_f32 v[40:41], v[40:41], v[116:117]
	v_pk_mul_f32 v[36:37], v[36:37], v[120:121]
	v_pk_mul_f32 v[46:47], v[46:47], v[114:115]
	v_pk_mul_f32 v[42:43], v[42:43], v[118:119]
	v_pk_mul_f32 v[38:39], v[38:39], v[122:123]
	v_pk_mul_f32 v[34:35], v[34:35], v[126:127]
	v_pk_mul_f32 v[32:33], v[32:33], v[124:125]
